# final RMSNorm loop software-pipelined: all of a row's loads issued one row ahead instead of 8 serialized load-wait-store round trips
# speedup vs baseline: 1.0015x; 1.0015x over previous
.LBB0_1430:
	v_readlane_b32 s2, v249, 4
	v_readlane_b32 s3, v249, 5
	v_readlane_b32 s11, v249, 10
	v_readfirstlane_b32 s0, v0
	s_ashr_i32 s0, s0, 6
	s_add_i32 s10, s0, s11
	s_cmpk_gt_i32 s10, 0x7fff
	s_cbranch_scc1 .LBB0_1433
	s_load_dwordx4 s[4:7], s[2:3], 0xb0
	s_load_dwordx2 s[8:9], s[2:3], 0xc0
	v_and_b32_e32 v36, 63, v0
	v_mov_b32_e32 v33, 0
	v_lshlrev_b32_e32 v32, 4, v36
	s_waitcnt lgkmcnt(0)
	v_lshl_add_u64 v[16:17], s[4:5], 0, v[32:33]
	v_add_co_u32_e32 v34, vcc, 0x1000, v16
	global_load_dwordx4 v[0:3], v32, s[4:5]
	global_load_dwordx4 v[4:7], v32, s[4:5] offset:1024
	global_load_dwordx4 v[8:11], v32, s[4:5] offset:2048
	global_load_dwordx4 v[12:15], v32, s[4:5] offset:3072
	v_addc_co_u32_e32 v35, vcc, 0, v17, vcc
	global_load_dwordx4 v[16:19], v[34:35], off
	global_load_dwordx4 v[20:23], v[34:35], off offset:1024
	global_load_dwordx4 v[24:27], v[34:35], off offset:2048
	global_load_dwordx4 v[28:31], v[34:35], off offset:3072
	s_ashr_i32 s1, s0, 31
	s_ashr_i32 s2, s11, 31
	s_add_u32 s0, s0, s11
	s_addc_u32 s1, s1, s2
	s_lshl_b64 s[2:3], s[0:1], 5
	s_add_u32 s2, s8, s2
	s_addc_u32 s3, s9, s3
	s_add_u32 s2, s2, 0x4dc00010
	s_addc_u32 s3, s3, 0
	s_ashr_i32 s23, s22, 31
	s_lshl_b64 s[4:5], s[22:23], 5
	s_lshl_b64 s[12:13], s[0:1], 13
	s_add_u32 s6, s6, s12
	s_addc_u32 s7, s7, s13
	v_lshl_add_u64 v[34:35], s[6:7], 0, v[32:33]
	s_mov_b64 s[6:7], 0x1000
	v_lshl_add_u64 v[34:35], v[34:35], 0, s[6:7]
	s_lshl_b64 s[6:7], s[22:23], 13
	s_lshl_b64 s[0:1], s[0:1], 12
	s_add_u32 s0, s8, s0
	v_lshlrev_b32_e32 v32, 3, v36
	s_addc_u32 s1, s9, s1
	v_lshl_add_u64 v[36:37], s[0:1], 0, v[32:33]
	s_mov_b64 s[0:1], 0x21c00800
	v_lshl_add_u64 v[36:37], v[36:37], 0, s[0:1]
	s_lshl_b64 s[8:9], s[22:23], 12
	v_mov_b32_e32 v32, 0x358637bd
	s_mov_b32 s11, 0xf800000
	v_mov_b32_e32 v38, 0x260
	global_load_dwordx4 v[52:55], v33, s[2:3] offset:-16
	global_load_dwordx4 v[56:59], v33, s[2:3]
	global_load_dwordx2 v[60:61], v[36:37], off offset:-2048
	global_load_dwordx2 v[62:63], v[36:37], off offset:-1536
	global_load_dwordx2 v[64:65], v[36:37], off offset:-1024
	global_load_dwordx2 v[66:67], v[36:37], off offset:-512
	global_load_dwordx2 v[68:69], v[36:37], off
	global_load_dwordx2 v[70:71], v[36:37], off offset:512
	global_load_dwordx2 v[72:73], v[36:37], off offset:1024
	global_load_dwordx2 v[74:75], v[36:37], off offset:1536
	s_waitcnt vmcnt(0)
.Lfn_loop:
	v_mov_b64_e32 v[40:41], v[52:53]
	v_mov_b64_e32 v[42:43], v[54:55]
	v_mov_b64_e32 v[44:45], v[56:57]
	v_mov_b64_e32 v[46:47], v[58:59]
	v_mov_b64_e32 v[80:81], v[60:61]
	v_mov_b64_e32 v[82:83], v[62:63]
	v_mov_b64_e32 v[84:85], v[64:65]
	v_mov_b64_e32 v[86:87], v[66:67]
	v_mov_b64_e32 v[88:89], v[68:69]
	v_mov_b64_e32 v[90:91], v[70:71]
	v_mov_b64_e32 v[92:93], v[72:73]
	v_mov_b64_e32 v[94:95], v[74:75]
	s_add_i32 s10, s10, s22
	s_add_u32 s2, s2, s4
	s_addc_u32 s3, s3, s5
	v_lshl_add_u64 v[36:37], v[36:37], 0, s[8:9]
	s_cmp_lt_i32 s10, 0x8000
	s_cbranch_scc0 .Lfn_noload
	global_load_dwordx4 v[52:55], v33, s[2:3] offset:-16
	global_load_dwordx4 v[56:59], v33, s[2:3]
	global_load_dwordx2 v[60:61], v[36:37], off offset:-2048
	global_load_dwordx2 v[62:63], v[36:37], off offset:-1536
	global_load_dwordx2 v[64:65], v[36:37], off offset:-1024
	global_load_dwordx2 v[66:67], v[36:37], off offset:-512
	global_load_dwordx2 v[68:69], v[36:37], off
	global_load_dwordx2 v[70:71], v[36:37], off offset:512
	global_load_dwordx2 v[72:73], v[36:37], off offset:1024
	global_load_dwordx2 v[74:75], v[36:37], off offset:1536
.Lfn_noload:
	v_mov_b32_e32 v50, v40
	v_mov_b32_e32 v51, v44
	v_mov_b32_e32 v44, v41
	v_mov_b32_e32 v40, v42
	v_mov_b32_e32 v41, v46
	v_mov_b32_e32 v46, v43
	v_pk_add_f32 v[44:45], v[50:51], v[44:45]
	v_pk_add_f32 v[40:41], v[40:41], v[46:47]
	v_pk_add_f32 v[40:41], v[44:45], v[40:41]
	v_add_f32_e32 v39, v40, v41
	v_fmamk_f32 v39, v39, 0x3a000000, v32
	v_mul_f32_e32 v40, 0x4f800000, v39
	v_cmp_gt_f32_e32 vcc, s11, v39
	s_nop 1
	v_cndmask_b32_e32 v39, v39, v40, vcc
	v_sqrt_f32_e32 v40, v39
	s_nop 0
	v_add_u32_e32 v41, -1, v40
	v_add_u32_e32 v44, 1, v40
	v_fma_f32 v45, -v41, v40, v39
	v_fma_f32 v46, -v44, v40, v39
	v_cmp_ge_f32_e64 s[0:1], 0, v45
	s_nop 1
	v_cndmask_b32_e64 v40, v40, v41, s[0:1]
	v_cmp_lt_f32_e64 s[0:1], 0, v46
	s_nop 1
	v_cndmask_b32_e64 v40, v40, v44, s[0:1]
	v_mul_f32_e32 v41, 0x37800000, v40
	v_cndmask_b32_e32 v40, v40, v41, vcc
	v_cmp_class_f32_e32 vcc, v39, v38
	s_nop 1
	v_cndmask_b32_e32 v39, v40, v39, vcc
	v_div_scale_f32 v40, s[0:1], v39, v39, 1.0
	v_rcp_f32_e32 v44, v40
	v_div_scale_f32 v41, vcc, 1.0, v39, 1.0
	v_fma_f32 v45, -v40, v44, 1.0
	v_fmac_f32_e32 v44, v45, v44
	v_mul_f32_e32 v45, v41, v44
	v_fma_f32 v46, -v40, v45, v41
	v_fmac_f32_e32 v45, v46, v44
	v_fma_f32 v40, -v40, v45, v41
	v_div_fmas_f32 v40, v40, v44, v45
	v_div_fixup_f32 v44, v40, v39, 1.0
	v_lshlrev_b32_e32 v42, 16, v80
	v_and_b32_e32 v43, 0xffff0000, v80
	v_lshlrev_b32_e32 v48, 16, v81
	v_and_b32_e32 v49, 0xffff0000, v81
	v_pk_mul_f32 v[46:47], v[44:45], v[42:43] op_sel_hi:[0,1]
	v_pk_mul_f32 v[42:43], v[44:45], v[48:49] op_sel_hi:[0,1]
	v_pk_mul_f32 v[102:103], v[2:3], v[42:43]
	v_pk_mul_f32 v[100:101], v[0:1], v[46:47]
	global_store_dwordx4 v[34:35], v[100:103], off offset:-4096
	v_lshlrev_b32_e32 v42, 16, v82
	v_and_b32_e32 v43, 0xffff0000, v82
	v_lshlrev_b32_e32 v48, 16, v83
	v_and_b32_e32 v49, 0xffff0000, v83
	v_pk_mul_f32 v[46:47], v[44:45], v[42:43] op_sel_hi:[0,1]
	v_pk_mul_f32 v[42:43], v[44:45], v[48:49] op_sel_hi:[0,1]
	v_pk_mul_f32 v[106:107], v[6:7], v[42:43]
	v_pk_mul_f32 v[104:105], v[4:5], v[46:47]
	global_store_dwordx4 v[34:35], v[104:107], off offset:-3072
	v_lshlrev_b32_e32 v42, 16, v84
	v_and_b32_e32 v43, 0xffff0000, v84
	v_lshlrev_b32_e32 v48, 16, v85
	v_and_b32_e32 v49, 0xffff0000, v85
	v_pk_mul_f32 v[46:47], v[44:45], v[42:43] op_sel_hi:[0,1]
	v_pk_mul_f32 v[42:43], v[44:45], v[48:49] op_sel_hi:[0,1]
	v_pk_mul_f32 v[110:111], v[10:11], v[42:43]
	v_pk_mul_f32 v[108:109], v[8:9], v[46:47]
	global_store_dwordx4 v[34:35], v[108:111], off offset:-2048
	v_lshlrev_b32_e32 v42, 16, v86
	v_and_b32_e32 v43, 0xffff0000, v86
	v_lshlrev_b32_e32 v48, 16, v87
	v_and_b32_e32 v49, 0xffff0000, v87
	v_pk_mul_f32 v[46:47], v[44:45], v[42:43] op_sel_hi:[0,1]
	v_pk_mul_f32 v[42:43], v[44:45], v[48:49] op_sel_hi:[0,1]
	v_pk_mul_f32 v[114:115], v[14:15], v[42:43]
	v_pk_mul_f32 v[112:113], v[12:13], v[46:47]
	global_store_dwordx4 v[34:35], v[112:115], off offset:-1024
	v_lshlrev_b32_e32 v42, 16, v88
	v_and_b32_e32 v43, 0xffff0000, v88
	v_lshlrev_b32_e32 v48, 16, v89
	v_and_b32_e32 v49, 0xffff0000, v89
	v_pk_mul_f32 v[46:47], v[44:45], v[42:43] op_sel_hi:[0,1]
	v_pk_mul_f32 v[42:43], v[44:45], v[48:49] op_sel_hi:[0,1]
	v_pk_mul_f32 v[118:119], v[18:19], v[42:43]
	v_pk_mul_f32 v[116:117], v[16:17], v[46:47]
	global_store_dwordx4 v[34:35], v[116:119], off
	v_lshlrev_b32_e32 v42, 16, v90
	v_and_b32_e32 v43, 0xffff0000, v90
	v_lshlrev_b32_e32 v48, 16, v91
	v_and_b32_e32 v49, 0xffff0000, v91
	v_pk_mul_f32 v[46:47], v[44:45], v[42:43] op_sel_hi:[0,1]
	v_pk_mul_f32 v[42:43], v[44:45], v[48:49] op_sel_hi:[0,1]
	v_pk_mul_f32 v[122:123], v[22:23], v[42:43]
	v_pk_mul_f32 v[120:121], v[20:21], v[46:47]
	global_store_dwordx4 v[34:35], v[120:123], off offset:1024
	v_lshlrev_b32_e32 v42, 16, v92
	v_and_b32_e32 v43, 0xffff0000, v92
	v_lshlrev_b32_e32 v48, 16, v93
	v_and_b32_e32 v49, 0xffff0000, v93
	v_pk_mul_f32 v[46:47], v[44:45], v[42:43] op_sel_hi:[0,1]
	v_pk_mul_f32 v[42:43], v[44:45], v[48:49] op_sel_hi:[0,1]
	v_pk_mul_f32 v[126:127], v[26:27], v[42:43]
	v_pk_mul_f32 v[124:125], v[24:25], v[46:47]
	global_store_dwordx4 v[34:35], v[124:127], off offset:2048
	v_lshlrev_b32_e32 v42, 16, v94
	v_and_b32_e32 v43, 0xffff0000, v94
	v_lshlrev_b32_e32 v48, 16, v95
	v_and_b32_e32 v49, 0xffff0000, v95
	v_pk_mul_f32 v[46:47], v[44:45], v[42:43] op_sel_hi:[0,1]
	v_pk_mul_f32 v[42:43], v[44:45], v[48:49] op_sel_hi:[0,1]
	v_pk_mul_f32 v[130:131], v[30:31], v[42:43]
	v_pk_mul_f32 v[128:129], v[28:29], v[46:47]
	global_store_dwordx4 v[34:35], v[128:131], off offset:3072
	v_lshl_add_u64 v[34:35], v[34:35], 0, s[6:7]
	s_cmp_lt_i32 s10, 0x8000
	s_cbranch_scc0 .LBB0_1433
	s_waitcnt vmcnt(8)
	s_branch .Lfn_loop
